# P2->P3 grid barrier also replaced by per-panel arrival counters (CNT word 3), on top of v088
# speedup vs baseline: 1.0209x; 1.0142x over previous
; __device__ __forceinline__ void mix_unit(LAS unsigned char* lds, const int wid, int n, int g, const bf16_t* __restrict__ UZ, const bf16_t* __restrict__ V, const float* __restrict__ vss, ...
;     const int tid = tid_of(wid), lane = tid & 63, r32 = lane & 31, hi = lane >> 5;
;     const size_t row0 = (size_t)n * CHUNK;
;     LAS float* rstdL = (LAS float*)(lds + 98304);
;     const int cc = tid & 31;
;     u32x4 uu[8];
; #pragma unroll
;     for (int i = 0; i < 8; ++i) { const int t = (tid >> 5) + 16 * i; uu[i] = __builtin_nontemporal_load((const u32x4*)(UZ + (row0 + t) * GW + g * GDIM + cc * 8)); }
;     {
;         u32x4 vr[8];
; #pragma unroll
;         for (int i = 0; i < 8; ++i) { const int c = tid + 512 * i, s = c >> 5, cc = c & 31;
;             vr[i] = __builtin_nontemporal_load((const u32x4*)(V + (row0 + s) * GW + g * GDIM + cc * 8)); }
;         if (tid < 128) rstdL[tid] = __builtin_amdgcn_rsqf(vss[row0 + tid] * (1.0f / GW) + EPS);
; #pragma unroll
;         for (int i = 0; i < 8; ++i) { const int c = tid + 512 * i, s = c >> 5, cc = c & 31;
;             *(LAS u32x4*)(lds + 32768 + (cc >> 4) * 32768 + off_b(s, cc & 15)) = vr[i]; }
;     }
;     __syncthreads();
; #pragma unroll
;     for (int i = 0; i < 4; ++i) { const int c = tid + 512 * i, t = c >> 4, ch = c & 15, s0 = ch * 8;
;         const f32x4 w0 = *(const f32x4*)(w_s + ((size_t)g * CHUNK + t) * CHUNK + s0), w1 = *(const f32x4*)(w_s + ((size_t)g * CHUNK + t) * CHUNK + s0 + 4);
;         float wv[8] = {w0[0], w0[1], w0[2], w0[3], w1[0], w1[1], w1[2], w1[3]};
; #pragma unroll
;         for (int j = 0; j < 8; ++j) wv[j] = (s0 + j <= t) ? wv[j] * rstdL[s0 + j] : 0.f;
;         u32x4 w; w.x = pk_bf16(wv[0], wv[1]); w.y = pk_bf16(wv[2], wv[3]); w.z = pk_bf16(wv[4], wv[5]); w.w = pk_bf16(wv[6], wv[7]);
;         *(LAS u32x4*)(lds + off_b(t, ch)) = w; }
;     __syncthreads();
;     f32x16 acc[4];
; #pragma unroll
;     for (int i = 0; i < 4; ++i)
; #pragma unroll
;         for (int r = 0; r < 16; ++r) acc[i][r] = 0.f;
;     {
;         const LAS unsigned char* vimg = lds + 32768 + (wid >> 2) * 32768;
;         const unsigned cblk = wid & 3, qa = (lane & 15) >> 2, blk = (lane >> 4) & 1, pp = lane & 3;
; #pragma unroll
;         for (int ks = 0; ks < 8; ++ks) {
;             const s16x4 lo = vtr(vimg + off_b(16 * ks + 8 * hi + qa, 4 * cblk + 2 * blk + (pp >> 1)) + 8 * (pp & 1));
.LBB0_261:
	v_readlane_b32 s4, v248, 0
	v_readlane_b32 s5, v248, 1
	s_cmp_lt_i32 s4, 3
	s_cselect_b64 s[4:5], -1, 0
	s_and_b64 s[74:75], s[4:5], s[0:1]
	s_andn2_b64 vcc, exec, s[74:75]
	v_readlane_b32 s6, v248, 2
	v_readlane_b32 s7, v248, 3
	s_cbranch_vccnz .LBB0_332
	s_cmpk_gt_i32 s2, 0x3ff
	s_cbranch_scc1 .LBB0_332
	v_mov_b32_e32 v1, 0
	v_lshlrev_b32_e32 v2, 4, v195
	v_writelane_b32 v248, s90, 45
	v_and_b32_e32 v2, 0x1f0, v2
	v_mov_b32_e32 v3, v1
	v_writelane_b32 v248, s92, 48
	v_ashrrev_i32_e32 v96, 5, v152
	v_add_u32_e32 v6, 0x200, v152
	v_lshl_add_u64 v[114:115], s[92:93], 0, v[2:3]
	v_add_u32_e32 v2, 0x800, v152
	v_ashrrev_i32_e32 v122, 5, v2
	v_add_u32_e32 v2, 0xa00, v152
	v_ashrrev_i32_e32 v124, 5, v2
	v_add_u32_e32 v2, 0xc00, v152
	v_ashrrev_i32_e32 v126, 5, v2
	v_add_u32_e32 v2, 0xe00, v152
	v_ashrrev_i32_e32 v128, 5, v2
	v_lshlrev_b32_e32 v2, 11, v195
	v_lshlrev_b32_e32 v3, 2, v96
	v_and_b32_e32 v2, 0x8000, v2
	v_and_b32_e32 v9, 15, v195
	v_and_b32_e32 v3, 12, v3
	v_bfe_u32 v11, v96, 2, 2
	v_ashrrev_i32_e32 v116, 5, v6
	v_add_u32_e32 v2, 0, v2
	v_bitop3_b32 v3, v3, v9, v11 bitop3:0x36
	v_lshl_add_u32 v11, v3, 4, v2
	v_lshlrev_b32_e32 v3, 2, v116
	v_add_u32_e32 v7, 0x400, v152
	v_and_b32_e32 v3, 12, v3
	v_bfe_u32 v13, v116, 2, 2
	v_ashrrev_i32_e32 v118, 5, v7
	v_bitop3_b32 v3, v3, v9, v13 bitop3:0x36
	v_lshl_add_u32 v13, v3, 4, v2
	v_lshlrev_b32_e32 v3, 2, v118
	v_add_u32_e32 v8, 0x600, v152
	v_and_b32_e32 v3, 12, v3
	v_bfe_u32 v15, v118, 2, 2
	v_ashrrev_i32_e32 v120, 5, v8
	v_bitop3_b32 v3, v3, v9, v15 bitop3:0x36
	v_lshl_add_u32 v15, v3, 4, v2
	v_lshlrev_b32_e32 v3, 2, v120
	v_and_b32_e32 v3, 12, v3
	v_bfe_u32 v17, v120, 2, 2
	v_bitop3_b32 v3, v3, v9, v17 bitop3:0x36
	v_lshl_add_u32 v17, v3, 4, v2
	v_lshlrev_b32_e32 v3, 2, v122
	s_mov_b64 s[8:9], s[80:81]
	v_and_b32_e32 v3, 12, v3
	v_bfe_u32 v19, v122, 2, 2
	v_writelane_b32 v248, s93, 49
	s_mov_b64 s[10:11], s[82:83]
	s_mov_b64 s[6:7], s[78:79]
	v_bitop3_b32 v3, v3, v9, v19 bitop3:0x36
	v_writelane_b32 v248, s4, 37
	v_lshl_add_u32 v19, v3, 4, v2
	v_lshlrev_b32_e32 v3, 2, v124
	v_writelane_b32 v248, s5, 38
	v_and_b32_e32 v3, 12, v3
	v_bfe_u32 v21, v124, 2, 2
	v_writelane_b32 v248, s6, 39
	v_bitop3_b32 v3, v3, v9, v21 bitop3:0x36
	v_writelane_b32 v248, s7, 40
	v_lshl_add_u32 v21, v3, 4, v2
	v_lshlrev_b32_e32 v3, 2, v126
	v_writelane_b32 v248, s8, 41
	v_and_b32_e32 v3, 12, v3
	v_bfe_u32 v23, v126, 2, 2
	v_writelane_b32 v248, s9, 42
	v_bitop3_b32 v3, v3, v9, v23 bitop3:0x36
	v_writelane_b32 v248, s10, 43
	v_lshl_add_u32 v23, v3, 4, v2
	v_lshlrev_b32_e32 v3, 2, v128
	v_ashrrev_i32_e32 v153, 31, v152
	v_writelane_b32 v248, s11, 44
	v_and_b32_e32 v3, 12, v3
	v_bfe_u32 v25, v128, 2, 2
	v_lshl_add_u64 v[130:131], v[152:153], 2, s[82:83]
	v_bitop3_b32 v3, v3, v9, v25 bitop3:0x36
	v_readlane_b32 s80, v248, 6
	v_lshl_add_u32 v25, v3, 4, v2
	v_lshlrev_b32_e32 v26, 3, v9
	v_lshlrev_b32_e32 v2, 5, v9
	v_mov_b32_e32 v3, v1
	v_readlane_b32 s88, v248, 14
	v_readlane_b32 s89, v248, 15
	v_ashrrev_i32_e32 v134, 4, v152
	s_add_i32 s18, 0, 0x18000
	v_lshl_add_u64 v[132:133], s[88:89], 0, v[2:3]
	v_or_b32_e32 v3, 3, v26
	v_lshlrev_b32_e32 v32, 2, v134
	v_ashrrev_i32_e32 v136, 4, v6
	v_ashrrev_i32_e32 v138, 4, v7
	v_ashrrev_i32_e32 v140, 4, v8
	v_cmp_le_i32_e64 s[8:9], v3, v134
	v_lshl_add_u32 v166, v3, 2, s18
	v_and_b32_e32 v32, 12, v32
	v_bfe_u32 v33, v134, 2, 2
	v_cmp_le_i32_e64 s[24:25], v3, v136
	v_cmp_le_i32_e64 s[42:43], v3, v138
	v_cmp_le_i32_e64 s[58:59], v3, v140
	s_bfe_u32 s63, s67, 0x20006
	v_lshrrev_b32_e32 v3, 3, v195
	v_and_b32_e32 v4, 31, v195
	v_or_b32_e32 v27, 4, v26
	v_bitop3_b32 v32, v32, v9, v33 bitop3:0x36
	v_lshlrev_b32_e32 v33, 2, v136
	s_lshl_b32 s64, s63, 2
	v_and_b32_e32 v3, 2, v3
	v_bfe_u32 v8, v195, 1, 1
	v_lshlrev_b32_e32 v0, 4, v4
	s_movk_i32 s0, 0x80
	v_add_u32_e32 v164, s18, v2
	v_or_b32_e32 v2, 2, v26
	v_cmp_le_i32_e64 s[10:11], v27, v134
	v_lshl_add_u32 v167, v27, 2, s18
	v_or_b32_e32 v28, 5, v26
	v_or_b32_e32 v29, 6, v26
	v_or_b32_e32 v30, 7, v26
	v_cmp_le_i32_e64 s[26:27], v27, v136
	v_and_b32_e32 v33, 12, v33
	v_bfe_u32 v34, v136, 2, 2
	v_cmp_le_i32_e64 s[44:45], v27, v138
	v_cmp_le_i32_e64 s[60:61], v27, v140
	v_or3_b32 v3, v3, s64, v8
	v_bfe_u32 v8, v195, 2, 2
	v_lshrrev_b32_e32 v27, 4, v195
	v_lshl_add_u64 v[98:99], s[20:21], 0, v[0:1]
	v_cmp_gt_i32_e32 vcc, s0, v152
	v_lshl_add_u32 v153, v152, 2, s18
	v_cmp_le_i32_e64 s[0:1], v26, v134
	v_cmp_lt_i32_e64 s[4:5], v26, v134
	v_cmp_le_i32_e64 s[6:7], v2, v134
	v_lshl_add_u32 v165, v2, 2, s18
	v_lshl_add_u32 v168, v28, 2, s18
	v_lshl_add_u32 v169, v29, 2, s18
	v_lshl_add_u32 v170, v30, 2, s18
	v_cmp_le_i32_e64 s[18:19], v26, v136
	v_cmp_lt_i32_e64 s[20:21], v26, v136
	v_cmp_le_i32_e64 s[22:23], v2, v136
	v_bitop3_b32 v33, v33, v9, v34 bitop3:0x36
	v_cmp_le_i32_e64 s[36:37], v26, v138
	v_cmp_lt_i32_e64 s[38:39], v26, v138
	v_cmp_le_i32_e64 s[40:41], v2, v138
	v_lshlrev_b32_e32 v34, 2, v138
	v_cmp_le_i32_e64 s[52:53], v26, v140
	v_cmp_lt_i32_e64 s[54:55], v26, v140
	v_cmp_le_i32_e64 s[56:57], v2, v140
	v_bfe_u32 v2, v195, 5, 1
	v_lshlrev_b32_e32 v26, 2, v8
	v_and_b32_e32 v27, 2, v27
	v_and_b32_e32 v34, 12, v34
	v_bfe_u32 v35, v138, 2, 2
	s_lshr_b32 s62, s67, 8
	v_bitop3_b32 v27, v26, v3, v27 bitop3:0x36
	v_lshl_or_b32 v26, v2, 1, v26
	v_bitop3_b32 v34, v34, v9, v35 bitop3:0x36
	s_lshl_b32 s64, s62, 15
	v_lshlrev_b32_e32 v35, 8, v8
	v_bitop3_b32 v3, v26, v3, 1 bitop3:0x36
	s_add_i32 s64, s64, 0
	v_lshl_or_b32 v35, v2, 11, v35
	v_lshlrev_b32_e32 v3, 4, v3
	v_add3_u32 v26, s64, v3, v35
	v_lshlrev_b32_e32 v3, 2, v140
	v_and_b32_e32 v3, 12, v3
	v_bfe_u32 v36, v140, 2, 2
	v_lshlrev_b32_e32 v5, 3, v195
; #define LAS __attribute__((address_space(3)))
; __device__ __forceinline__ s16x4 vtr(const LAS unsigned char* p) { return __builtin_bit_cast(s16x4, __builtin_amdgcn_ds_read_tr16_b64_v4i16((LAS s16x4*)p)); }
; __device__ __forceinline__ int crow(int r, int hi) { return (r & 3) + 8 * (r >> 2) + 4 * hi; }
; #define tid tid_of(wave)
; #define lane lane_id()
; __device__ __forceinline__ void mix_unit(LAS unsigned char* lds, const int wid, int n, int g, const bf16_t* __restrict__ UZ, const bf16_t* __restrict__ V, const float* __restrict__ vss, ...
;     ...
;         const LAS unsigned char* vimg = lds + 32768 + (wid >> 2) * 32768;
;         const unsigned cblk = wid & 3, qa = (lane & 15) >> 2, blk = (lane >> 4) & 1, pp = lane & 3;
; #pragma unroll
;         for (int ks = 0; ks < 8; ++ks) {
;             const s16x4 lo = vtr(vimg + off_b(16 * ks + 8 * hi + qa, 4 * cblk + 2 * blk + (pp >> 1)) + 8 * (pp & 1));
;             const s16x4 hh = vtr(vimg + off_b(16 * ks + 8 * hi + 4 + qa, 4 * cblk + 2 * blk + (pp >> 1)) + 8 * (pp & 1));
;             const bf16x8 vf = (bf16x8){lo[0], lo[1], lo[2], lo[3], hh[0], hh[1], hh[2], hh[3]};
; #pragma unroll
;             for (int i = 0; i < 4; ++i) if (ks <= 2 * i + 1) {
;                 const bf16x8 af = *(const LAS bf16x8*)(lds + off_b(32 * i + r32, 2 * ks + hi));
;                 acc[i] = __builtin_amdgcn_mfma_f32_32x32x16_bf16(af, vf, acc[i], 0, 0, 0);
;             }
;         }
;     }
;     __syncthreads();
;     {
;         LAS float* mx = (LAS float*)lds;
;         const int c = 128 * (wid >> 2) + 32 * (wid & 3) + r32;
; #pragma unroll
;         for (int i = 0; i < 4; ++i)
; #pragma unroll
;             for (int r = 0; r < 16; ++r) mx[(32 * i + crow(r, hi)) * 256 + c] = acc[i][r];
;     }
;     __syncthreads();
;     {
;         const f32x4 g0 = *(const f32x4*)(vg + g * GDIM + cc * 8), g1 = *(const f32x4*)(vg + g * GDIM + cc * 8 + 4);
;         float bb[8];
; #pragma unroll
;         for (int i = 0; i < 8; ++i) bb[i] = b_s[g * CHUNK + (tid >> 5) + 16 * i];
; #pragma unroll
;         for (int i = 0; i < 8; ++i) { const int t = (tid >> 5) + 16 * i;
;             const f32x4 m0 = *(const LAS f32x4*)(lds + (t * 256 + cc * 8) * 4), m1 = *(const LAS f32x4*)(lds + (t * 256 + cc * 8 + 4) * 4);
	v_bitop3_b32 v3, v3, v9, v36 bitop3:0x36
	v_lshlrev_b32_e32 v27, 4, v27
	v_and_b32_e32 v5, 8, v5
	s_lshl_b32 s62, s62, 9
	s_lshl_b32 s63, s63, 7
	v_lshl_add_u32 v9, v3, 4, 0
	v_lshlrev_b32_e32 v3, 2, v4
	v_add3_u32 v27, s64, v27, v5
	s_or_b32 s64, s63, s62
	v_and_b32_e32 v36, 12, v3
	v_readlane_b32 s81, v248, 7
	v_readlane_b32 s82, v248, 8
	v_readlane_b32 s83, v248, 9
	v_readlane_b32 s84, v248, 10
	v_readlane_b32 s85, v248, 11
	v_readlane_b32 s86, v248, 12
	v_readlane_b32 s87, v248, 13
	v_readlane_b32 s90, v248, 16
	v_readlane_b32 s91, v248, 17
	v_readlane_b32 s92, v248, 18
	v_readlane_b32 s93, v248, 19
	v_readlane_b32 s94, v248, 20
	v_readlane_b32 s95, v248, 21
	v_writelane_b32 v248, s67, 47
	v_bitop3_b32 v38, v36, v2, v8 bitop3:0x36
	v_or_b32_e32 v39, 2, v2
	v_or_b32_e32 v40, 4, v2
	v_or_b32_e32 v41, 6, v2
	v_or_b32_e32 v42, 8, v2
	v_or_b32_e32 v43, 10, v2
	v_or_b32_e32 v44, 12, v2
	v_or_b32_e32 v45, 14, v2
	v_lshlrev_b32_e32 v2, 12, v2
	s_add_i32 s64, s64, 0
	v_add3_u32 v171, s64, v2, v3
	v_readlane_b32 s64, v248, 25
	v_add_u32_e32 v100, 16, v96
	v_add_u32_e32 v102, 32, v96
	v_add_u32_e32 v104, 48, v96
	v_add_u32_e32 v106, 64, v96
	v_add_u32_e32 v108, 0x50, v96
	v_add_u32_e32 v110, 0x60, v96
	v_add_u32_e32 v112, 0x70, v96
	v_bitop3_b32 v39, v36, v39, v8 bitop3:0x36
	v_bitop3_b32 v40, v36, v40, v8 bitop3:0x36
	v_bitop3_b32 v41, v36, v41, v8 bitop3:0x36
	v_bitop3_b32 v42, v36, v42, v8 bitop3:0x36
	v_bitop3_b32 v43, v36, v43, v8 bitop3:0x36
	v_bitop3_b32 v44, v36, v44, v8 bitop3:0x36
	v_bitop3_b32 v8, v36, v45, v8 bitop3:0x36
	v_lshlrev_b32_e32 v2, 5, v4
	v_mov_b32_e32 v3, v1
	v_readlane_b32 s65, v248, 26
	v_lshlrev_b32_e32 v10, 8, v96
	v_lshlrev_b32_e32 v12, 8, v116
	v_lshlrev_b32_e32 v14, 8, v118
	v_lshlrev_b32_e32 v16, 8, v120
	v_lshlrev_b32_e32 v18, 8, v122
	v_lshlrev_b32_e32 v20, 8, v124
	v_lshlrev_b32_e32 v22, 8, v126
	v_lshlrev_b32_e32 v24, 8, v128
	v_cmp_le_i32_e64 s[12:13], v28, v134
	v_lshlrev_b32_e32 v31, 8, v134
	v_lshl_add_u32 v32, v32, 4, 0
	v_cmp_le_i32_e64 s[28:29], v28, v136
	v_lshlrev_b32_e32 v6, 8, v136
	v_lshl_add_u32 v33, v33, 4, 0
	v_cmp_le_i32_e64 s[46:47], v28, v138
	v_lshlrev_b32_e32 v7, 8, v138
	v_lshl_add_u32 v34, v34, 4, 0
	v_cmp_le_i32_e64 s[62:63], v28, v140
	v_lshlrev_b32_e32 v28, 8, v140
	v_lshl_add_u32 v37, v4, 8, 0
	v_lshlrev_b32_e32 v38, 4, v38
	v_lshlrev_b32_e32 v39, 4, v39
	v_lshlrev_b32_e32 v40, 4, v40
	v_lshlrev_b32_e32 v41, 4, v41
	v_lshlrev_b32_e32 v42, 4, v42
	v_lshlrev_b32_e32 v43, 4, v43
	v_lshlrev_b32_e32 v44, 4, v44
	v_lshlrev_b32_e32 v8, 4, v8
	v_lshl_add_u64 v[142:143], s[86:87], 0, v[2:3]
	v_add_u32_e32 v2, 0, v2
	v_lshl_add_u64 v[144:145], s[64:65], 0, v[0:1]
	v_lshlrev_b32_e32 v0, 10, v96
	v_lshlrev_b32_e32 v1, 10, v100
	v_lshlrev_b32_e32 v3, 10, v102
	v_lshlrev_b32_e32 v4, 10, v104
	v_lshlrev_b32_e32 v36, 10, v106
	v_lshlrev_b32_e32 v45, 10, v108
	v_lshlrev_b32_e32 v46, 10, v110
	v_lshlrev_b32_e32 v47, 10, v112
	v_ashrrev_i32_e32 v97, 31, v96
	v_ashrrev_i32_e32 v101, 31, v100
	v_ashrrev_i32_e32 v103, 31, v102
	v_ashrrev_i32_e32 v105, 31, v104
	v_ashrrev_i32_e32 v107, 31, v106
	v_ashrrev_i32_e32 v109, 31, v108
	v_ashrrev_i32_e32 v111, 31, v110
	v_ashrrev_i32_e32 v113, 31, v112
	v_ashrrev_i32_e32 v117, 31, v116
	v_ashrrev_i32_e32 v119, 31, v118
	v_ashrrev_i32_e32 v121, 31, v120
	v_ashrrev_i32_e32 v123, 31, v122
	v_ashrrev_i32_e32 v125, 31, v124
	v_ashrrev_i32_e32 v127, 31, v126
	v_ashrrev_i32_e32 v129, 31, v128
	s_mov_b32 s77, 0
	v_ashrrev_i32_e32 v135, 31, v134
	v_cmp_le_i32_e64 s[14:15], v29, v134
	v_cmp_le_i32_e64 s[16:17], v30, v134
	v_ashrrev_i32_e32 v137, 31, v136
	v_cmp_le_i32_e64 s[30:31], v29, v136
	v_cmp_le_i32_e64 s[34:35], v30, v136
	v_ashrrev_i32_e32 v139, 31, v138
	v_cmp_le_i32_e64 s[48:49], v29, v138
	v_cmp_le_i32_e64 s[50:51], v30, v138
	v_ashrrev_i32_e32 v141, 31, v140
	v_add_u32_e32 v172, 0x10000, v171
	v_add_u32_e32 v173, 0x10400, v171
	v_add_u32_e32 v174, 0x10800, v171
	v_add_u32_e32 v175, 0x10c00, v171
	v_add_u32_e32 v176, 0x12000, v171
	v_add_u32_e32 v177, 0x12400, v171
	v_add_u32_e32 v178, 0x12800, v171
	v_add_u32_e32 v179, 0x12c00, v171
	v_add_u32_e32 v180, 0x14000, v171
	v_add_u32_e32 v181, 0x14400, v171
	v_add_u32_e32 v182, 0x14800, v171
	v_add_u32_e32 v183, 0x14c00, v171
	v_add_u32_e32 v184, 0x16000, v171
	v_add_u32_e32 v185, 0x16400, v171
	v_add_u32_e32 v186, 0x16800, v171
	v_add_u32_e32 v187, 0x16c00, v171
	v_add_u32_e32 v188, 0x18000, v171
	v_add_u32_e32 v189, 0x18400, v171
	v_add_u32_e32 v190, 0x18800, v171
	v_add_u32_e32 v191, 0x18c00, v171
	v_add_u32_e32 v192, 0x1a000, v171
	v_add_u32_e32 v193, 0x1a400, v171
	v_add_u32_e32 v194, 0x1a800, v171
	v_add_u32_e32 v196, 0x1ac00, v171
	v_add_u32_e32 v197, 0x1c000, v171
	v_add_u32_e32 v198, 0x1c400, v171
	v_add_u32_e32 v199, 0x1c800, v171
	v_add_u32_e32 v200, 0x1cc00, v171
	v_add_u32_e32 v201, 0x1e000, v171
	v_add_u32_e32 v202, 0x1e400, v171
	v_add_u32_e32 v203, 0x1e800, v171
	v_add_u32_e32 v204, 0x1ec00, v171
	v_mov_b32_e32 v205, 0x358637bd
	v_add_u32_e32 v206, v11, v10
	v_add_u32_e32 v207, v13, v12
	v_add_u32_e32 v208, v15, v14
	v_add_u32_e32 v209, v17, v16
	v_add_u32_e32 v210, v19, v18
	v_add_u32_e32 v211, v21, v20
	v_add_u32_e32 v212, v23, v22
	v_add_u32_e32 v213, v25, v24
	v_add_u32_e32 v214, v32, v31
	v_add_u32_e32 v215, v33, v6
	v_add_u32_e32 v216, v34, v7
	v_add_u32_e32 v217, v9, v28
	v_add_u32_e32 v218, v27, v35
	v_add_u32_e32 v219, v26, v5
	v_add_u32_e32 v220, v37, v38
	v_add_u32_e32 v221, v37, v39
	v_add_u32_e32 v222, v37, v40
	v_add_u32_e32 v223, v37, v41
	v_add_u32_e32 v224, v37, v42
	v_add_u32_e32 v225, v37, v43
	v_add_u32_e32 v226, v37, v44
	v_add_u32_e32 v227, v37, v8
	v_add_u32_e32 v228, v2, v0
	v_add_u32_e32 v229, v2, v1
	v_add_u32_e32 v230, v2, v3
	v_add_u32_e32 v231, v2, v4
	v_add_u32_e32 v232, v2, v36
	v_add_u32_e32 v233, v2, v45
	v_add_u32_e32 v234, v2, v46
	v_add_u32_e32 v235, v2, v47
	s_mov_b32 s71, s2
	v_cmp_le_i32_e64 s[64:65], v29, v140
	v_cmp_le_i32_e64 s[66:67], v30, v140
	s_mov_b32 s78, -1
	s_branch .LBB0_265
; #define LAS __attribute__((address_space(3)))
; __device__ __forceinline__ s16x4 vtr(const LAS unsigned char* p) { return __builtin_bit_cast(s16x4, __builtin_amdgcn_ds_read_tr16_b64_v4i16((LAS s16x4*)p)); }
; __device__ __forceinline__ int crow(int r, int hi) { return (r & 3) + 8 * (r >> 2) + 4 * hi; }
; #define tid tid_of(wave)
; #define lane lane_id()
; __device__ __forceinline__ void mix_unit(LAS unsigned char* lds, const int wid, int n, int g, const bf16_t* __restrict__ UZ, const bf16_t* __restrict__ V, const float* __restrict__ vss, ...
;     ...
;         const LAS unsigned char* vimg = lds + 32768 + (wid >> 2) * 32768;
;         const unsigned cblk = wid & 3, qa = (lane & 15) >> 2, blk = (lane >> 4) & 1, pp = lane & 3;
; #pragma unroll
;         for (int ks = 0; ks < 8; ++ks) {
;             const s16x4 lo = vtr(vimg + off_b(16 * ks + 8 * hi + qa, 4 * cblk + 2 * blk + (pp >> 1)) + 8 * (pp & 1));
;             const s16x4 hh = vtr(vimg + off_b(16 * ks + 8 * hi + 4 + qa, 4 * cblk + 2 * blk + (pp >> 1)) + 8 * (pp & 1));
;             const bf16x8 vf = (bf16x8){lo[0], lo[1], lo[2], lo[3], hh[0], hh[1], hh[2], hh[3]};
; #pragma unroll
;             for (int i = 0; i < 4; ++i) if (ks <= 2 * i + 1) {
;                 const bf16x8 af = *(const LAS bf16x8*)(lds + off_b(32 * i + r32, 2 * ks + hi));
;                 acc[i] = __builtin_amdgcn_mfma_f32_32x32x16_bf16(af, vf, acc[i], 0, 0, 0);
;             }
;         }
;     }
;     __syncthreads();
;     {
;         LAS float* mx = (LAS float*)lds;
;         const int c = 128 * (wid >> 2) + 32 * (wid & 3) + r32;
; #pragma unroll
;         for (int i = 0; i < 4; ++i)
; #pragma unroll
;             for (int r = 0; r < 16; ++r) mx[(32 * i + crow(r, hi)) * 256 + c] = acc[i][r];
;     }
;     __syncthreads();
;     {
;         const f32x4 g0 = *(const f32x4*)(vg + g * GDIM + cc * 8), g1 = *(const f32x4*)(vg + g * GDIM + cc * 8 + 4);
;         float bb[8];
; #pragma unroll
;         for (int i = 0; i < 8; ++i) bb[i] = b_s[g * CHUNK + (tid >> 5) + 16 * i];
.Lp2_mfma:
	ds_read_b64_tr_b16 v[0:1], v218 offset:32768
	ds_read_b64_tr_b16 v[2:3], v219 offset:33792
	ds_read_b128 v[4:7], v220
	s_waitcnt lgkmcnt(0)
	v_mfma_f32_32x32x16_bf16 v[48:63], v[4:7], v[0:3], 0
	ds_read_b128 v[4:7], v220 offset:8192
	s_lshl_b32 s72, s97, 8
	s_lshl_b32 s82, s72, 2
	s_mov_b32 s83, s77
	s_waitcnt lgkmcnt(0)
	v_mfma_f32_32x32x16_bf16 v[32:47], v[4:7], v[0:3], 0
	ds_read_b128 v[4:7], v220 offset:16384
	s_waitcnt lgkmcnt(0)
	v_mfma_f32_32x32x16_bf16 v[16:31], v[4:7], v[0:3], 0
	ds_read_b128 v[4:7], v220 offset:24576
	ds_read_b64_tr_b16 v[236:237], v218 offset:36864
	ds_read_b64_tr_b16 v[238:239], v219 offset:37888
	ds_read_b128 v[240:243], v221
	s_waitcnt lgkmcnt(0)
	v_mfma_f32_32x32x16_bf16 v[48:63], v[240:243], v[236:239], v[48:63]
	ds_read_b128 v[240:243], v221 offset:8192
	s_waitcnt lgkmcnt(0)
	v_mfma_f32_32x32x16_bf16 v[32:47], v[240:243], v[236:239], v[32:47]
	ds_read_b128 v[240:243], v221 offset:16384
	s_waitcnt lgkmcnt(0)
	v_mfma_f32_32x32x16_bf16 v[16:31], v[240:243], v[236:239], v[16:31]
	ds_read_b128 v[240:243], v221 offset:24576
	v_mfma_f32_32x32x16_bf16 v[0:15], v[4:7], v[0:3], 0
	s_waitcnt lgkmcnt(0)
	v_mfma_f32_32x32x16_bf16 v[0:15], v[240:243], v[236:239], v[0:15]
	ds_read_b64_tr_b16 v[236:237], v218 offset:40960
	ds_read_b64_tr_b16 v[238:239], v219 offset:41984
	ds_read_b128 v[240:243], v222 offset:8192
	s_waitcnt lgkmcnt(0)
	v_mfma_f32_32x32x16_bf16 v[32:47], v[240:243], v[236:239], v[32:47]
	ds_read_b128 v[240:243], v222 offset:16384
	s_waitcnt lgkmcnt(0)
	v_mfma_f32_32x32x16_bf16 v[16:31], v[240:243], v[236:239], v[16:31]
	ds_read_b128 v[240:243], v222 offset:24576
	s_waitcnt lgkmcnt(0)
	v_mfma_f32_32x32x16_bf16 v[0:15], v[240:243], v[236:239], v[0:15]
	ds_read_b64_tr_b16 v[236:237], v218 offset:45056
	ds_read_b64_tr_b16 v[238:239], v219 offset:46080
	ds_read_b128 v[240:243], v223 offset:8192
	s_waitcnt lgkmcnt(0)
	v_mfma_f32_32x32x16_bf16 v[32:47], v[240:243], v[236:239], v[32:47]
	ds_read_b128 v[240:243], v223 offset:16384
	s_waitcnt lgkmcnt(0)
	v_mfma_f32_32x32x16_bf16 v[16:31], v[240:243], v[236:239], v[16:31]
	ds_read_b128 v[240:243], v223 offset:24576
	s_waitcnt lgkmcnt(0)
	v_mfma_f32_32x32x16_bf16 v[0:15], v[240:243], v[236:239], v[0:15]
	ds_read_b64_tr_b16 v[236:237], v218 offset:49152
	ds_read_b64_tr_b16 v[238:239], v219 offset:50176
	ds_read_b128 v[240:243], v224 offset:16384
	s_waitcnt lgkmcnt(0)
	v_mfma_f32_32x32x16_bf16 v[16:31], v[240:243], v[236:239], v[16:31]
	ds_read_b128 v[240:243], v224 offset:24576
	s_waitcnt lgkmcnt(0)
	v_mfma_f32_32x32x16_bf16 v[0:15], v[240:243], v[236:239], v[0:15]
	ds_read_b64_tr_b16 v[236:237], v218 offset:53248
	ds_read_b64_tr_b16 v[238:239], v219 offset:54272
	ds_read_b128 v[240:243], v225 offset:16384
	s_waitcnt lgkmcnt(0)
	v_mfma_f32_32x32x16_bf16 v[16:31], v[240:243], v[236:239], v[16:31]
	ds_read_b128 v[240:243], v225 offset:24576
	s_waitcnt lgkmcnt(0)
	v_mfma_f32_32x32x16_bf16 v[0:15], v[240:243], v[236:239], v[0:15]
	ds_read_b64_tr_b16 v[236:237], v218 offset:57344
	ds_read_b64_tr_b16 v[238:239], v219 offset:58368
	ds_read_b128 v[240:243], v226 offset:24576
	s_waitcnt lgkmcnt(0)
	v_mfma_f32_32x32x16_bf16 v[0:15], v[240:243], v[236:239], v[0:15]
	ds_read_b64_tr_b16 v[236:237], v218 offset:61440
	ds_read_b64_tr_b16 v[238:239], v219 offset:62464
	ds_read_b128 v[240:243], v227 offset:24576
	s_waitcnt lgkmcnt(0)
	s_barrier
	v_mfma_f32_32x32x16_bf16 v[0:15], v[240:243], v[236:239], v[0:15]
	ds_write2st64_b32 v171, v48, v49 offset1:4
	ds_write2st64_b32 v171, v50, v51 offset0:8 offset1:12
	ds_write2st64_b32 v171, v52, v53 offset0:32 offset1:36
	ds_write2st64_b32 v171, v54, v55 offset0:40 offset1:44
	ds_write2st64_b32 v171, v56, v57 offset0:64 offset1:68
	ds_write2st64_b32 v171, v58, v59 offset0:72 offset1:76
	ds_write2st64_b32 v171, v60, v61 offset0:96 offset1:100
	ds_write2st64_b32 v171, v62, v63 offset0:104 offset1:108
	ds_write2st64_b32 v171, v32, v33 offset0:128 offset1:132
	ds_write2st64_b32 v171, v34, v35 offset0:136 offset1:140
	ds_write2st64_b32 v171, v36, v37 offset0:160 offset1:164
	ds_write2st64_b32 v171, v38, v39 offset0:168 offset1:172
	ds_write2st64_b32 v171, v40, v41 offset0:192 offset1:196
	ds_write2st64_b32 v171, v42, v43 offset0:200 offset1:204
	ds_write2st64_b32 v171, v44, v45 offset0:224 offset1:228
	ds_write2st64_b32 v171, v46, v47 offset0:232 offset1:236
	ds_write_b32 v172, v16
	ds_write_b32 v173, v17
	ds_write_b32 v174, v18
	ds_write_b32 v175, v19
	ds_write_b32 v176, v20
	ds_write_b32 v177, v21
	ds_write_b32 v178, v22
	ds_write_b32 v179, v23
	ds_write_b32 v180, v24
	ds_write_b32 v181, v25
	ds_write_b32 v182, v26
	ds_write_b32 v183, v27
	ds_write_b32 v184, v28
	ds_write_b32 v185, v29
	ds_write_b32 v186, v30
	ds_write_b32 v187, v31
	ds_write_b32 v188, v0
	ds_write_b32 v189, v1
	ds_write_b32 v190, v2
	ds_write_b32 v191, v3
	ds_write_b32 v192, v4
	ds_write_b32 v193, v5
	ds_write_b32 v194, v6
	ds_write_b32 v196, v7
	ds_write_b32 v197, v8
	ds_write_b32 v198, v9
	ds_write_b32 v199, v10
	ds_write_b32 v200, v11
	ds_write_b32 v201, v12
	ds_write_b32 v202, v13
	ds_write_b32 v203, v14
	ds_write_b32 v204, v15
	v_lshl_add_u64 v[4:5], v[142:143], 0, s[82:83]
	s_waitcnt lgkmcnt(0)
	s_barrier
	s_waitcnt vmcnt(0)
	global_load_dwordx4 v[0:3], v[4:5], off offset:16
	s_nop 0
	global_load_dwordx4 v[4:7], v[4:5], off
	v_add_u32_e32 v8, s76, v96
	v_readlane_b32 s80, v248, 6
	v_ashrrev_i32_e32 v9, 31, v8
	v_readlane_b32 s90, v248, 16
	v_readlane_b32 s91, v248, 17
	v_lshlrev_b32_e32 v26, 16, v92
	s_lshl_b32 s76, s72, 1
	v_lshl_add_u64 v[8:9], v[8:9], 2, s[90:91]
	global_load_dword v18, v[8:9], off
	global_load_dword v19, v[8:9], off offset:64
	global_load_dword v20, v[8:9], off offset:128
	global_load_dword v21, v[8:9], off offset:192
	global_load_dword v22, v[8:9], off offset:256
	global_load_dword v23, v[8:9], off offset:320
	global_load_dword v24, v[8:9], off offset:384
	global_load_dword v25, v[8:9], off offset:448
	s_cmp_lt_i32 s78, 0
	s_cbranch_scc1 .Lp2_noarr_g
	s_lshl_b32 s98, s78, 8
	s_add_i32 s98, s98, 12
	v_mov_b32_e32 v236, s98
	v_mov_b32_e32 v237, 1
	v_readlane_b32 s98, v248, 43
	v_readlane_b32 s99, v248, 44
	s_add_u32 s98, s98, 0x310000
	s_addc_u32 s99, s99, 0
	s_mov_b64 s[100:101], exec
	s_mov_b64 exec, 1
	global_atomic_add v236, v237, s[98:99]
	s_mov_b64 exec, s[100:101]
; #define LAS __attribute__((address_space(3)))
; __device__ __forceinline__ unsigned pk_bf16(float lo, float hi) { return pg8::cvt_pk_bf16(lo, hi); }
; __device__ __forceinline__ float bf_lo(unsigned w) { return __uint_as_float(w << 16); }
; __device__ __forceinline__ float bf_hi(unsigned w) { return __uint_as_float(w & 0xffff0000u); }
; #define tid tid_of(wave)
; __device__ __forceinline__ void mix_unit(LAS unsigned char* lds, const int wid, int n, int g, const bf16_t* __restrict__ UZ, const bf16_t* __restrict__ V, const float* __restrict__ vss, ...
;     ...
;     {
;         const f32x4 g0 = *(const f32x4*)(vg + g * GDIM + cc * 8), g1 = *(const f32x4*)(vg + g * GDIM + cc * 8 + 4);
;         float bb[8];
; #pragma unroll
;         for (int i = 0; i < 8; ++i) bb[i] = b_s[g * CHUNK + (tid >> 5) + 16 * i];
; #pragma unroll
;         for (int i = 0; i < 8; ++i) { const int t = (tid >> 5) + 16 * i;
;             const f32x4 m0 = *(const LAS f32x4*)(lds + (t * 256 + cc * 8) * 4), m1 = *(const LAS f32x4*)(lds + (t * 256 + cc * 8 + 4) * 4);
;             float y[8];
;             y[0] = bf_lo(uu[i].x) * (m0[0] * g0[0] + bb[i]); y[1] = bf_hi(uu[i].x) * (m0[1] * g0[1] + bb[i]);
;             y[2] = bf_lo(uu[i].y) * (m0[2] * g0[2] + bb[i]); y[3] = bf_hi(uu[i].y) * (m0[3] * g0[3] + bb[i]);
;             y[4] = bf_lo(uu[i].z) * (m1[0] * g1[0] + bb[i]); y[5] = bf_hi(uu[i].z) * (m1[1] * g1[1] + bb[i]);
;             y[6] = bf_lo(uu[i].w) * (m1[2] * g1[2] + bb[i]); y[7] = bf_hi(uu[i].w) * (m1[3] * g1[3] + bb[i]);
;             u32x4 w; w.x = pk_bf16(y[0], y[1]); w.y = pk_bf16(y[2], y[3]); w.z = pk_bf16(y[4], y[5]); w.w = pk_bf16(y[6], y[7]);
;             *(u32x4*)(Y + (row0 + t) * GW + g * GDIM + cc * 8) = w; }
.Lp2_noarr_g:
	s_lshr_b32 s78, s71, 5
	ds_read_b128 v[10:13], v228
	ds_read_b128 v[14:17], v228 offset:16
	v_lshl_add_u64 v[8:9], v[144:145], 0, s[76:77]
	v_readlane_b32 s88, v248, 14
	v_readlane_b32 s89, v248, 15
	v_readlane_b32 s88, v248, 35
	s_add_i32 s71, s71, s88
	v_readlane_b32 s89, v248, 36
	s_cmpk_lt_i32 s71, 0x400
	v_readlane_b32 s81, v248, 7
	v_readlane_b32 s82, v248, 8
	v_readlane_b32 s83, v248, 9
	v_readlane_b32 s84, v248, 10
	v_readlane_b32 s85, v248, 11
	v_readlane_b32 s86, v248, 12
	v_readlane_b32 s87, v248, 13
	v_readlane_b32 s92, v248, 18
	v_readlane_b32 s93, v248, 19
	v_readlane_b32 s94, v248, 20
	v_readlane_b32 s95, v248, 21
	s_waitcnt vmcnt(7) lgkmcnt(0)
	v_fma_f32 v14, v0, v14, v18
	v_fma_f32 v10, v4, v10, v18
	v_mul_f32_e32 v10, v10, v26
	v_and_b32_e32 v26, 0xffff0000, v92
	v_fma_f32 v11, v5, v11, v18
	v_mul_f32_e32 v11, v11, v26
	v_lshlrev_b32_e32 v26, 16, v93
	v_fma_f32 v12, v6, v12, v18
	v_mul_f32_e32 v12, v12, v26
	v_and_b32_e32 v26, 0xffff0000, v93
	v_fma_f32 v13, v7, v13, v18
	v_mul_f32_e32 v13, v13, v26
	v_lshlrev_b32_e32 v26, 16, v94
	v_mul_f32_e32 v14, v14, v26
	v_and_b32_e32 v26, 0xffff0000, v94
	v_fma_f32 v15, v1, v15, v18
	v_mul_f32_e32 v15, v15, v26
	v_lshlrev_b32_e32 v26, 16, v95
	v_fma_f32 v16, v2, v16, v18
	v_mul_f32_e32 v16, v16, v26
	v_and_b32_e32 v26, 0xffff0000, v95
	v_fmac_f32_e32 v18, v3, v17
	v_cvt_pk_bf16_f32 v10, v10, v11
	v_cvt_pk_bf16_f32 v11, v12, v13
	v_cvt_pk_bf16_f32 v12, v14, v15
	v_lshl_add_u64 v[14:15], v[8:9], 0, v[162:163]
	v_mul_f32_e32 v17, v18, v26
	v_cvt_pk_bf16_f32 v13, v16, v17
	global_store_dwordx4 v[14:15], v[10:13], off sc1
	ds_read_b128 v[10:13], v229
	ds_read_b128 v[14:17], v229 offset:16
	v_lshlrev_b32_e32 v18, 16, v88
	s_waitcnt vmcnt(7) lgkmcnt(1)
	v_fma_f32 v10, v4, v10, v19
	v_mul_f32_e32 v10, v10, v18
	v_and_b32_e32 v18, 0xffff0000, v88
	v_fma_f32 v11, v5, v11, v19
	v_mul_f32_e32 v11, v11, v18
	v_lshlrev_b32_e32 v18, 16, v89
	v_fma_f32 v12, v6, v12, v19
	v_mul_f32_e32 v12, v12, v18
	v_and_b32_e32 v18, 0xffff0000, v89
	v_fma_f32 v13, v7, v13, v19
	v_mul_f32_e32 v13, v13, v18
	v_lshlrev_b32_e32 v18, 16, v90
	s_waitcnt lgkmcnt(0)
	v_fma_f32 v14, v0, v14, v19
	v_mul_f32_e32 v14, v14, v18
	v_and_b32_e32 v18, 0xffff0000, v90
	v_fma_f32 v15, v1, v15, v19
	v_mul_f32_e32 v15, v15, v18
	v_lshlrev_b32_e32 v18, 16, v91
	v_fma_f32 v16, v2, v16, v19
	v_mul_f32_e32 v16, v16, v18
	v_and_b32_e32 v18, 0xffff0000, v91
	v_fmac_f32_e32 v19, v3, v17
	v_cvt_pk_bf16_f32 v10, v10, v11
	v_cvt_pk_bf16_f32 v11, v12, v13
	v_cvt_pk_bf16_f32 v12, v14, v15
	v_lshl_add_u64 v[14:15], v[8:9], 0, v[160:161]
	v_mul_f32_e32 v17, v19, v18
	v_cvt_pk_bf16_f32 v13, v16, v17
	global_store_dwordx4 v[14:15], v[10:13], off sc1
	ds_read_b128 v[10:13], v230
	ds_read_b128 v[14:17], v230 offset:16
	v_lshlrev_b32_e32 v18, 16, v84
	s_waitcnt vmcnt(7) lgkmcnt(1)
	v_fma_f32 v10, v4, v10, v20
	v_mul_f32_e32 v10, v10, v18
	v_and_b32_e32 v18, 0xffff0000, v84
	v_fma_f32 v11, v5, v11, v20
	v_mul_f32_e32 v11, v11, v18
	v_lshlrev_b32_e32 v18, 16, v85
	v_fma_f32 v12, v6, v12, v20
	v_mul_f32_e32 v12, v12, v18
	v_and_b32_e32 v18, 0xffff0000, v85
	v_fma_f32 v13, v7, v13, v20
	v_mul_f32_e32 v13, v13, v18
	v_lshlrev_b32_e32 v18, 16, v86
	s_waitcnt lgkmcnt(0)
	v_fma_f32 v14, v0, v14, v20
	v_mul_f32_e32 v14, v14, v18
	v_and_b32_e32 v18, 0xffff0000, v86
	v_fma_f32 v15, v1, v15, v20
	v_mul_f32_e32 v15, v15, v18
	v_lshlrev_b32_e32 v18, 16, v87
	v_fma_f32 v16, v2, v16, v20
	v_mul_f32_e32 v16, v16, v18
	v_and_b32_e32 v18, 0xffff0000, v87
	v_fmac_f32_e32 v20, v3, v17
	v_cvt_pk_bf16_f32 v10, v10, v11
	v_cvt_pk_bf16_f32 v11, v12, v13
	v_cvt_pk_bf16_f32 v12, v14, v15
	v_lshl_add_u64 v[14:15], v[8:9], 0, v[158:159]
	v_mul_f32_e32 v17, v20, v18
	v_cvt_pk_bf16_f32 v13, v16, v17
	global_store_dwordx4 v[14:15], v[10:13], off sc1
	ds_read_b128 v[10:13], v231
	ds_read_b128 v[14:17], v231 offset:16
	v_lshlrev_b32_e32 v18, 16, v80
	s_waitcnt vmcnt(7) lgkmcnt(1)
	v_fma_f32 v10, v4, v10, v21
	v_mul_f32_e32 v10, v10, v18
	v_and_b32_e32 v18, 0xffff0000, v80
	v_fma_f32 v11, v5, v11, v21
	v_mul_f32_e32 v11, v11, v18
	v_lshlrev_b32_e32 v18, 16, v81
	v_fma_f32 v12, v6, v12, v21
	v_mul_f32_e32 v12, v12, v18
	v_and_b32_e32 v18, 0xffff0000, v81
	v_fma_f32 v13, v7, v13, v21
	v_mul_f32_e32 v13, v13, v18
	v_lshlrev_b32_e32 v18, 16, v82
	s_waitcnt lgkmcnt(0)
; #define LAS __attribute__((address_space(3)))
; __device__ __forceinline__ unsigned pk_bf16(float lo, float hi) { return pg8::cvt_pk_bf16(lo, hi); }
; __device__ __forceinline__ float bf_lo(unsigned w) { return __uint_as_float(w << 16); }
; __device__ __forceinline__ float bf_hi(unsigned w) { return __uint_as_float(w & 0xffff0000u); }
; #define tid tid_of(wave)
; __device__ __forceinline__ void mix_unit(LAS unsigned char* lds, const int wid, int n, int g, const bf16_t* __restrict__ UZ, const bf16_t* __restrict__ V, const float* __restrict__ vss, ...
;     ...
;         for (int i = 0; i < 8; ++i) { const int t = (tid >> 5) + 16 * i;
;             const f32x4 m0 = *(const LAS f32x4*)(lds + (t * 256 + cc * 8) * 4), m1 = *(const LAS f32x4*)(lds + (t * 256 + cc * 8 + 4) * 4);
;             float y[8];
;             y[0] = bf_lo(uu[i].x) * (m0[0] * g0[0] + bb[i]); y[1] = bf_hi(uu[i].x) * (m0[1] * g0[1] + bb[i]);
;             y[2] = bf_lo(uu[i].y) * (m0[2] * g0[2] + bb[i]); y[3] = bf_hi(uu[i].y) * (m0[3] * g0[3] + bb[i]);
;             y[4] = bf_lo(uu[i].z) * (m1[0] * g1[0] + bb[i]); y[5] = bf_hi(uu[i].z) * (m1[1] * g1[1] + bb[i]);
;             y[6] = bf_lo(uu[i].w) * (m1[2] * g1[2] + bb[i]); y[7] = bf_hi(uu[i].w) * (m1[3] * g1[3] + bb[i]);
;             u32x4 w; w.x = pk_bf16(y[0], y[1]); w.y = pk_bf16(y[2], y[3]); w.z = pk_bf16(y[4], y[5]); w.w = pk_bf16(y[6], y[7]);
;             *(u32x4*)(Y + (row0 + t) * GW + g * GDIM + cc * 8) = w; }
;     }
;     __syncthreads();
	v_fma_f32 v14, v0, v14, v21
	v_mul_f32_e32 v14, v14, v18
	v_and_b32_e32 v18, 0xffff0000, v82
	v_fma_f32 v15, v1, v15, v21
	v_mul_f32_e32 v15, v15, v18
	v_lshlrev_b32_e32 v18, 16, v83
	v_fma_f32 v16, v2, v16, v21
	v_mul_f32_e32 v16, v16, v18
	v_and_b32_e32 v18, 0xffff0000, v83
	v_fmac_f32_e32 v21, v3, v17
	v_cvt_pk_bf16_f32 v10, v10, v11
	v_cvt_pk_bf16_f32 v11, v12, v13
	v_cvt_pk_bf16_f32 v12, v14, v15
	v_lshl_add_u64 v[14:15], v[8:9], 0, v[156:157]
	v_mul_f32_e32 v17, v21, v18
	v_cvt_pk_bf16_f32 v13, v16, v17
	global_store_dwordx4 v[14:15], v[10:13], off sc1
	ds_read_b128 v[10:13], v232
	ds_read_b128 v[14:17], v232 offset:16
	v_lshlrev_b32_e32 v18, 16, v76
	s_waitcnt vmcnt(7) lgkmcnt(1)
	v_fma_f32 v10, v4, v10, v22
	v_mul_f32_e32 v10, v10, v18
	v_and_b32_e32 v18, 0xffff0000, v76
	v_fma_f32 v11, v5, v11, v22
	v_mul_f32_e32 v11, v11, v18
	v_lshlrev_b32_e32 v18, 16, v77
	v_fma_f32 v12, v6, v12, v22
	v_mul_f32_e32 v12, v12, v18
	v_and_b32_e32 v18, 0xffff0000, v77
	v_fma_f32 v13, v7, v13, v22
	v_mul_f32_e32 v13, v13, v18
	v_lshlrev_b32_e32 v18, 16, v78
	s_waitcnt lgkmcnt(0)
	v_fma_f32 v14, v0, v14, v22
	v_mul_f32_e32 v14, v14, v18
	v_and_b32_e32 v18, 0xffff0000, v78
	v_fma_f32 v15, v1, v15, v22
	v_mul_f32_e32 v15, v15, v18
	v_lshlrev_b32_e32 v18, 16, v79
	v_fma_f32 v16, v2, v16, v22
	v_mul_f32_e32 v16, v16, v18
	v_and_b32_e32 v18, 0xffff0000, v79
	v_fmac_f32_e32 v22, v3, v17
	v_cvt_pk_bf16_f32 v10, v10, v11
	v_cvt_pk_bf16_f32 v11, v12, v13
	v_cvt_pk_bf16_f32 v12, v14, v15
	v_lshl_add_u64 v[14:15], v[8:9], 0, v[154:155]
	v_mul_f32_e32 v17, v22, v18
	v_cvt_pk_bf16_f32 v13, v16, v17
	global_store_dwordx4 v[14:15], v[10:13], off sc1
	ds_read_b128 v[10:13], v233
	ds_read_b128 v[14:17], v233 offset:16
	v_lshlrev_b32_e32 v18, 16, v72
	s_waitcnt vmcnt(7) lgkmcnt(1)
	v_fma_f32 v10, v4, v10, v23
	v_mul_f32_e32 v10, v10, v18
	v_and_b32_e32 v18, 0xffff0000, v72
	v_fma_f32 v11, v5, v11, v23
	v_mul_f32_e32 v11, v11, v18
	v_lshlrev_b32_e32 v18, 16, v73
	v_fma_f32 v12, v6, v12, v23
	v_mul_f32_e32 v12, v12, v18
	v_and_b32_e32 v18, 0xffff0000, v73
	v_fma_f32 v13, v7, v13, v23
	v_mul_f32_e32 v13, v13, v18
	v_lshlrev_b32_e32 v18, 16, v74
	s_waitcnt lgkmcnt(0)
	v_fma_f32 v14, v0, v14, v23
	v_mul_f32_e32 v14, v14, v18
	v_and_b32_e32 v18, 0xffff0000, v74
	v_fma_f32 v15, v1, v15, v23
	v_mul_f32_e32 v15, v15, v18
	v_lshlrev_b32_e32 v18, 16, v75
	v_fma_f32 v16, v2, v16, v23
	v_mul_f32_e32 v16, v16, v18
	v_and_b32_e32 v18, 0xffff0000, v75
	v_fmac_f32_e32 v23, v3, v17
	v_cvt_pk_bf16_f32 v10, v10, v11
	v_cvt_pk_bf16_f32 v11, v12, v13
	v_cvt_pk_bf16_f32 v12, v14, v15
	v_lshl_add_u64 v[14:15], v[8:9], 0, v[150:151]
	v_mul_f32_e32 v17, v23, v18
	v_cvt_pk_bf16_f32 v13, v16, v17
	global_store_dwordx4 v[14:15], v[10:13], off sc1
	ds_read_b128 v[10:13], v234
	ds_read_b128 v[14:17], v234 offset:16
	v_lshlrev_b32_e32 v18, 16, v68
	s_waitcnt vmcnt(7) lgkmcnt(1)
	v_fma_f32 v10, v4, v10, v24
	v_mul_f32_e32 v10, v10, v18
	v_and_b32_e32 v18, 0xffff0000, v68
	v_fma_f32 v11, v5, v11, v24
	v_mul_f32_e32 v11, v11, v18
	v_lshlrev_b32_e32 v18, 16, v69
	v_fma_f32 v12, v6, v12, v24
	v_mul_f32_e32 v12, v12, v18
	v_and_b32_e32 v18, 0xffff0000, v69
	v_fma_f32 v13, v7, v13, v24
	v_mul_f32_e32 v13, v13, v18
	v_lshlrev_b32_e32 v18, 16, v70
	s_waitcnt lgkmcnt(0)
	v_fma_f32 v14, v0, v14, v24
	v_mul_f32_e32 v14, v14, v18
	v_and_b32_e32 v18, 0xffff0000, v70
	v_fma_f32 v15, v1, v15, v24
	v_mul_f32_e32 v15, v15, v18
	v_lshlrev_b32_e32 v18, 16, v71
	v_fma_f32 v16, v2, v16, v24
	v_mul_f32_e32 v16, v16, v18
	v_and_b32_e32 v18, 0xffff0000, v71
	v_fmac_f32_e32 v24, v3, v17
	v_cvt_pk_bf16_f32 v10, v10, v11
	v_cvt_pk_bf16_f32 v11, v12, v13
	v_cvt_pk_bf16_f32 v12, v14, v15
	v_lshl_add_u64 v[14:15], v[8:9], 0, v[148:149]
	v_mul_f32_e32 v17, v24, v18
	v_cvt_pk_bf16_f32 v13, v16, v17
	global_store_dwordx4 v[14:15], v[10:13], off sc1
	ds_read_b128 v[10:13], v235
	ds_read_b128 v[14:17], v235 offset:16
	v_lshlrev_b32_e32 v18, 16, v64
	s_waitcnt vmcnt(7) lgkmcnt(1)
	v_fma_f32 v4, v4, v10, v25
	v_and_b32_e32 v10, 0xffff0000, v64
	v_fma_f32 v5, v5, v11, v25
	v_mul_f32_e32 v5, v5, v10
	v_lshlrev_b32_e32 v10, 16, v65
	v_fma_f32 v6, v6, v12, v25
	v_mul_f32_e32 v6, v6, v10
	v_and_b32_e32 v10, 0xffff0000, v65
	v_fma_f32 v7, v7, v13, v25
	v_mul_f32_e32 v7, v7, v10
	v_lshlrev_b32_e32 v10, 16, v66
	s_waitcnt lgkmcnt(0)
	v_fma_f32 v0, v0, v14, v25
	v_mul_f32_e32 v10, v0, v10
	v_and_b32_e32 v0, 0xffff0000, v66
	v_fma_f32 v1, v1, v15, v25
	v_mul_f32_e32 v11, v1, v0
	v_lshlrev_b32_e32 v0, 16, v67
	v_fma_f32 v1, v2, v16, v25
	v_mul_f32_e32 v4, v4, v18
	v_mul_f32_e32 v12, v1, v0
	v_and_b32_e32 v0, 0xffff0000, v67
	v_fmac_f32_e32 v25, v3, v17
	v_mul_f32_e32 v3, v25, v0
	v_cvt_pk_bf16_f32 v0, v4, v5
	v_lshl_add_u64 v[4:5], v[8:9], 0, v[146:147]
	v_cvt_pk_bf16_f32 v1, v6, v7
	v_cvt_pk_bf16_f32 v2, v10, v11
	v_cvt_pk_bf16_f32 v3, v12, v3
	global_store_dwordx4 v[4:5], v[0:3], off sc1
	s_barrier
	s_cbranch_scc0 .LBB0_331

; __global__ void __launch_bounds__(NWAVES * 64, 2) fwd_kernel(Args a) {
;     ...
;         for (int it = vcu; it < (NTOK / CHUNK) * NGRP; it += G) mix_unit(lds, wave, it >> 4, it & 15, U, V, VSS, a_w_s, a_b_s, a_vg, Y);
.LBB0_331:
	s_waitcnt vmcnt(0)
	s_cmp_lt_i32 s78, 0
	s_cbranch_scc1 .Lp2_noarr_x
	s_lshl_b32 s98, s78, 8
	s_add_i32 s98, s98, 12
	v_mov_b32_e32 v236, s98
	v_mov_b32_e32 v237, 1
	v_readlane_b32 s98, v248, 43
	v_readlane_b32 s99, v248, 44
	s_add_u32 s98, s98, 0x310000
	s_addc_u32 s99, s99, 0
	s_mov_b64 s[100:101], exec
	s_mov_b64 exec, 1
	global_atomic_add v236, v237, s[98:99]
	s_mov_b64 exec, s[100:101]

; __device__ __forceinline__ int tid_of(int wave) { return wave * 64 + lane_id(); }
; __device__ __forceinline__ unsigned xb_ld(unsigned* p)              { return __hip_atomic_load(p, __ATOMIC_RELAXED, __HIP_MEMORY_SCOPE_AGENT); }
; __device__ __forceinline__ unsigned xb_add(unsigned* p, unsigned v) { return __hip_atomic_fetch_add(p, v, __ATOMIC_RELAXED, __HIP_MEMORY_SCOPE_AGENT); }
; #define XB_SPIN(cond, bar) do { unsigned _sp = 0; while (cond) { __builtin_amdgcn_s_sleep(1); \
;     if ((++_sp & 255u) == 0u) { if (xb_ld(&(bar)[XB_TMO])) break; if (_sp > XB_SPIN_CAP) { atomicAdd(&(bar)[XB_TMO], 1u); break; } } } } while (0)
; __device__ __forceinline__ void xcd_barrier(const XcdBarrier& b) {
;     asm volatile("s_waitcnt vmcnt(0)" ::: "memory");
;     __syncthreads();
;     if (tid_of(b.w) == 0) {
;         unsigned* bar = b.bar;
;         __builtin_amdgcn_s_waitcnt(0);
;         unsigned nloc = b.st[0], nx = b.st[1];
;         if (nloc == 0u) { xcd_barrier_complete(bar, b.x, nloc, nx); b.st[0] = nloc; b.st[1] = nx; }
;         const unsigned old = xb_add(&bar[XB_XSUB(b.x)], 1u);
;         const unsigned gen = old / nloc;
;         if (old + 1u == (gen + 1u) * nloc) {
;             __builtin_amdgcn_fence(__ATOMIC_RELEASE, "agent");
;             asm volatile("s_waitcnt vmcnt(0)" ::: "memory");
;             const unsigned og = xb_add(&bar[XB_TOP], 1u);
;             const unsigned tg = og / nx;
;             if (og + 1u == (tg + 1u) * nx) xb_add(&bar[XB_TOPGEN], 1u);
;             else XB_SPIN(xb_ld(&bar[XB_TOPGEN]) == tg, bar);
;             __builtin_amdgcn_fence(__ATOMIC_ACQUIRE, "agent");
;             xb_add(&bar[XB_XGEN(b.x)], 1u);
;             asm volatile("s_waitcnt vmcnt(0)" ::: "memory");
;         } else {
;             XB_SPIN(xb_ld(&bar[XB_XGEN(b.x)]) == gen, bar);
;             __builtin_amdgcn_fence(__ATOMIC_ACQUIRE, "agent");
;             asm volatile("s_waitcnt vmcnt(0)" ::: "memory");
;         }
;     }
;     __syncthreads();
; }
.LBB0_332:
	v_readlane_b32 s4, v248, 0
	v_readlane_b32 s5, v248, 1
	s_cmp_gt_i32 s5, 3
	s_cselect_b64 s[0:1], -1, 0
	s_and_b64 s[4:5], s[74:75], s[0:1]
	v_readlane_b32 s76, v248, 4
	s_andn2_b64 vcc, exec, s[4:5]
	v_readlane_b32 s77, v248, 5
	v_readlane_b32 s6, v248, 2
	v_readlane_b32 s7, v248, 3
	v_readlane_b32 s98, v248, 35
	s_cmpk_eq_i32 s98, 0x100
	s_cbranch_scc1 .LBB0_386
	s_cbranch_vccnz .LBB0_386
	s_waitcnt vmcnt(0)
	s_waitcnt vmcnt(0) lgkmcnt(0)
	s_barrier
	s_and_saveexec_b64 s[4:5], s[76:77]
	s_cbranch_execz .LBB0_385
	s_add_i32 s6, 0, 0x24fe0
	v_mov_b32_e32 v0, s6
	s_waitcnt vmcnt(0) expcnt(0) lgkmcnt(0)
	ds_read_b32 v2, v0
	s_add_i32 s6, 0, 0x24fe4
	v_mov_b32_e32 v0, s6
	ds_read_b32 v0, v0
	s_waitcnt lgkmcnt(1)
	v_cmp_ne_u32_e32 vcc, 0, v2
	s_cbranch_vccnz .LBB0_349
	s_add_u32 s6, s68, 0x1000
	s_addc_u32 s7, s69, 0
	s_add_u32 s8, s68, 0x1100
	s_addc_u32 s9, s69, 0
	s_add_u32 s10, s68, 0x1200
	s_addc_u32 s11, s69, 0
	s_mul_i32 s20, s89, s90
	s_add_u32 s12, s68, 0x1300
	s_mul_i32 s20, s20, s88
	s_addc_u32 s13, s69, 0
	s_mov_b32 s21, 1
	v_mov_b32_e32 v16, 0
	s_branch .LBB0_337

; #define PG8_STAGE(bufoff, gbase, voff) do { _Pragma("unroll") for (int _i = 0; _i < 2; ++_i) \
;         __builtin_amdgcn_global_load_lds((const unsigned*)((const char*)(gbase) + (voff)[_i]), (PG8_LAS unsigned*)(lds + (bufoff) + ldsw + _i * 8192), 16, 0, 0); } while (0)
; #define PG8_BAR __builtin_amdgcn_s_barrier()
; #define tid tid_of(wave)
; template <class Epi, class Sched, bool ALIGN_EPI = false, bool SP2 = false>
; __device__ __forceinline__ void gemm_phase(PG8_LAS unsigned char* lds, const Gemm g, const Sched& S, const Epi& E, const int wave_) {
;     ...
;     for (int i = 0; i < 2; ++i) { int R, C; stage_rc(tid * 16 + i * 8192, R, C); const int Rb = Epi::PERM ? ((R & ~31) + perm32(R & 31)) : R;
;         voffA[i] = (unsigned)(R * K + C) * 2u; voffB[i] = (unsigned)(Rb * K + C) * 2u; }
;     const size_t kstep = (size_t)(BK * 2);
;     const size_t hstep = (size_t)HALF * K * 2;
;     const size_t tstep = 2 * hstep;
;     const unsigned ldsw = (unsigned)wid * 1024u;
;     const int aoff = lds_byte(wr * 64 + fr, fq * 8), boff = lds_byte(wc * 32 + fr, fq * 8);
;     ...
;     Unit cur, nxt; int ui = 0;
;     if (!S.next(0, cur)) return;
;     f32x4 acc[2][2][4][2];
; #pragma unroll
;     for (int a = 0; a < 2; ++a)
; #pragma unroll
;         for (int b = 0; b < 2; ++b)
; #pragma unroll
;             for (int m = 0; m < 4; ++m)
; #pragma unroll
;                 for (int n = 0; n < 2; ++n) acc[a][b][m][n] = (f32x4){0.f, 0.f, 0.f, 0.f};
;     bf16x8 At[4][2], B0[2][2], B1[2][2];
;     const char* cA = (const char*)g.A + (size_t)cur.pm * tstep; const char* cB = (const char*)g.Bt + (size_t)cur.pn * tstep;
;     S.a_ready(cur);
;     if constexpr (SP2) {
;         PG8_STAGE(PG8_SB(0, 0), cB, voffB); PG8_STAGE(PG8_SB(0, 1), cB + hstep, voffB); PG8_STAGE(PG8_SA(0, 0), cA, voffA); PG8_STAGE(PG8_SA(0, 1), cA + hstep, voffA);
;         if (wr == 1) PG8_BAR;
.LBB0_389:
	s_andn2_b64 vcc, exec, s[0:1]
	s_cbranch_vccnz .LBB0_425
	v_readlane_b32 s100, v248, 35
	s_cmpk_lg_i32 s100, 0x100
	s_cbranch_scc1 .Lp3_nowait
	v_readlane_b32 s100, v248, 0
	s_cmp_gt_i32 s100, 2
	s_cbranch_scc1 .Lp3_nowait
	s_lshl_b32 s98, s26, 8
	s_add_i32 s98, s98, 12
	v_mov_b32_e32 v236, s98
	s_add_u32 s98, s82, 0x310000
	s_addc_u32 s99, s83, 0
	s_mov_b32 s100, 0
.Lp3_poll:
	global_load_dword v237, v236, s[98:99] sc1
	s_waitcnt vmcnt(0)
	v_readfirstlane_b32 s101, v237
	s_cmpk_ge_u32 s101, 0x100
	s_cbranch_scc1 .Lp3_nowait
	s_add_i32 s100, s100, 1
	s_cmp_lt_u32 s100, 0x10000
	s_cbranch_scc0 .Lp3_nowait
	s_sleep 2
	s_branch .Lp3_poll
.Lp3_nowait:
	v_readlane_b32 s1, v248, 22
	s_lshl_b32 s36, s1, 10
	v_lshl_add_u32 v0, v195, 4, s36
	v_ashrrev_i32_e32 v1, 31, v0
	v_lshrrev_b32_e32 v1, 22, v1
	v_add_u32_e32 v1, v0, v1
	v_ashrrev_i32_e32 v8, 10, v1
	v_mul_i32_i24_e32 v1, 0x400, v8
	v_sub_u32_e32 v1, v0, v1
	v_lshrrev_b32_e32 v2, 4, v1
	v_bitop3_b32 v1, v2, v1, 32 bitop3:0x6c
	v_ashrrev_i32_e32 v3, 31, v1
	v_lshrrev_b32_e32 v3, 26, v3
	v_add_u32_e32 v3, v1, v3
	v_lshlrev_b32_e32 v2, 3, v8
	v_ashrrev_i32_e32 v9, 6, v3
	v_and_b32_e32 v3, 0xc0, v3
	v_and_b32_e32 v2, -16, v2
	v_sub_u32_e32 v1, v1, v3
	v_mov_b32_e32 v3, 1
	v_add_u32_e32 v2, v9, v2
	v_ashrrev_i16_sdwa v1, v3, sext(v1) dst_sel:DWORD dst_unused:UNUSED_PAD src0_sel:DWORD src1_sel:BYTE_0
	v_lshlrev_b32_e32 v4, 5, v8
	v_bfe_i32 v10, v1, 0, 16
	v_lshlrev_b32_e32 v1, 1, v2
	v_lshrrev_b32_e32 v5, 2, v2
	v_and_b32_e32 v6, 3, v9
	s_mov_b32 s1, 0x7ffe0
	v_and_b32_e32 v4, 32, v4
	v_and_b32_e32 v1, 24, v1
	v_and_b32_e32 v5, 4, v5
	v_and_or_b32 v6, v2, s1, v6
	v_or3_b32 v1, v6, v5, v1
	v_add_lshl_u32 v4, v4, v10, 1
	v_add_u32_e32 v0, 0x2000, v0
	v_lshl_add_u32 v156, v1, 13, v4
	v_ashrrev_i32_e32 v1, 31, v0
	v_lshrrev_b32_e32 v1, 22, v1
	v_add_u32_e32 v1, v0, v1
	v_ashrrev_i32_e32 v11, 10, v1
	v_mul_i32_i24_e32 v1, 0x400, v11
	v_sub_u32_e32 v0, v0, v1
	v_lshrrev_b32_e32 v1, 4, v0
	v_bitop3_b32 v0, v1, v0, 32 bitop3:0x6c
	v_lshl_add_u32 v154, v2, 13, v4
	v_ashrrev_i32_e32 v2, 31, v0
	v_lshrrev_b32_e32 v2, 26, v2
	v_add_u32_e32 v2, v0, v2
	v_ashrrev_i32_e32 v12, 6, v2
	v_and_b32_e32 v2, 0xffc0, v2
	s_lshr_b32 s0, s67, 8
	v_sub_u32_e32 v0, v0, v2
	v_lshrrev_b16_e32 v2, 7, v0
	s_cmp_eq_u32 s0, 1
	v_lshlrev_b32_e32 v1, 3, v11
	v_and_b32_e32 v2, 1, v2
	s_cselect_b64 s[10:11], -1, 0
	s_ashr_i32 s27, s26, 31
	s_ashr_i32 s25, s24, 31
	v_and_b32_e32 v1, -16, v1
	v_add_u16_e32 v0, v0, v2
	s_lshl_b64 s[4:5], s[26:27], 21
	s_lshl_b64 s[12:13], s[24:25], 21
	v_readlane_b32 s14, v248, 29
	v_add_u32_e32 v1, v12, v1
	v_ashrrev_i16_sdwa v0, v3, sext(v0) dst_sel:DWORD dst_unused:UNUSED_PAD src0_sel:DWORD src1_sel:BYTE_0
	v_readlane_b32 s15, v248, 30
	s_add_u32 s30, s14, s12
	v_lshlrev_b32_e32 v4, 5, v11
	v_bfe_i32 v13, v0, 0, 16
	v_lshlrev_b32_e32 v0, 1, v1
	v_lshrrev_b32_e32 v2, 2, v1
	v_and_b32_e32 v3, 3, v12
	s_addc_u32 s31, s15, s13
	s_add_i32 s27, s36, 0
	v_and_b32_e32 v4, 32, v4
	v_and_b32_e32 v0, 24, v0
	v_and_b32_e32 v2, 4, v2
	v_and_or_b32 v3, v1, s1, v3
	s_add_i32 m0, s27, 0x10000
	s_add_i32 s1, s27, 0x12000
	v_or3_b32 v0, v3, v2, v0
	v_add_lshl_u32 v2, v4, v13, 1
	s_add_u32 s12, s30, 0x100000
	v_lshl_add_u32 v160, v0, 13, v2
	s_addc_u32 s13, s31, 0
	s_add_i32 s14, s27, 0x14000
	s_add_i32 s15, s27, 0x16000
	v_readlane_b32 s16, v248, 25
	global_load_lds_dwordx4 v156, s[30:31]
	s_mov_b32 m0, s1
	v_readlane_b32 s17, v248, 26
	s_add_u32 s28, s16, s4
	global_load_lds_dwordx4 v160, s[30:31]
	s_mov_b32 m0, s14
	s_addc_u32 s29, s17, s5
	s_add_i32 s37, s27, 0x2000
	global_load_lds_dwordx4 v156, s[12:13]
	s_mov_b32 m0, s15
	s_add_u32 s4, s28, 0x100000
	global_load_lds_dwordx4 v160, s[12:13]
	s_mov_b32 m0, s27
	v_lshl_add_u32 v158, v1, 13, v2
	s_addc_u32 s5, s29, 0
	s_add_i32 s40, s27, 0x4000
	global_load_lds_dwordx4 v154, s[28:29]
	s_mov_b32 m0, s37
	s_add_i32 s41, s27, 0x6000
	global_load_lds_dwordx4 v158, s[28:29]
	s_mov_b32 m0, s40
	v_mov_b32_e32 v157, 0
	global_load_lds_dwordx4 v154, s[4:5]
	s_mov_b32 m0, s41
	v_mov_b32_e32 v161, v157
	global_load_lds_dwordx4 v158, s[4:5]
	v_mov_b32_e32 v155, v157
	v_mov_b32_e32 v159, v157
	s_mov_b32 s42, 0
	s_cmp_lg_u32 s0, 1
	v_lshl_add_u64 v[6:7], s[30:31], 0, v[156:157]
	v_lshl_add_u64 v[4:5], s[30:31], 0, v[160:161]
	v_lshl_add_u64 v[2:3], s[28:29], 0, v[154:155]
	v_lshl_add_u64 v[0:1], s[28:29], 0, v[158:159]
	s_cbranch_scc1 .LBB0_392
	s_barrier
